# v8 + layer-0 x->bf16 row pass: 8 row loads in flight per wave instead of load/convert/store serialised
# speedup vs baseline: 1.0023x; 1.0023x over previous
.LBB0_170:
	v_add_co_u32_e32 v20, vcc, 0xfffff000, v2
	s_nop 1
	v_addc_co_u32_e32 v21, vcc, -1, v3, vcc
	s_waitcnt lgkmcnt(0)
	global_load_dwordx4 v[12:15], v[20:21], off offset:-3072
	global_load_dwordx4 v[16:19], v[20:21], off offset:-2048
	global_load_dwordx4 v[20:23], v[20:21], off offset:-1024
	global_load_dwordx4 v[24:27], v[2:3], off offset:-4096
	global_load_dwordx4 v[28:31], v[2:3], off offset:-3072
	global_load_dwordx4 v[32:35], v[2:3], off offset:-2048
	global_load_dwordx4 v[36:39], v[2:3], off offset:-1024
	global_load_dwordx4 v[40:43], v[2:3], off
	s_waitcnt vmcnt(7)
	v_cvt_pk_bf16_f32 v44, v12, v13
	v_cvt_pk_bf16_f32 v45, v14, v15
	global_store_dwordx2 v[4:5], v[44:45], off offset:-2048
	v_mul_f32_e32 v0, v13, v13
	v_mul_f32_e32 v13, v15, v15
	v_fmac_f32_e32 v0, v12, v12
	v_fmac_f32_e32 v13, v14, v14
	v_add_f32_e32 v0, v0, v13
	s_waitcnt vmcnt(7)
	v_cvt_pk_bf16_f32 v46, v16, v17
	v_cvt_pk_bf16_f32 v47, v18, v19
	global_store_dwordx2 v[4:5], v[46:47], off offset:-1536
	v_mul_f32_e32 v12, v17, v17
	v_mul_f32_e32 v13, v19, v19
	v_fmac_f32_e32 v12, v16, v16
	v_fmac_f32_e32 v13, v18, v18
	v_add_f32_e32 v12, v12, v13
	v_add_f32_e32 v0, v0, v12
	s_waitcnt vmcnt(7)
	v_cvt_pk_bf16_f32 v48, v20, v21
	v_cvt_pk_bf16_f32 v49, v22, v23
	global_store_dwordx2 v[4:5], v[48:49], off offset:-1024
	v_mul_f32_e32 v12, v21, v21
	v_mul_f32_e32 v13, v23, v23
	v_fmac_f32_e32 v12, v20, v20
	v_fmac_f32_e32 v13, v22, v22
	v_add_f32_e32 v12, v12, v13
	v_add_f32_e32 v0, v0, v12
	s_waitcnt vmcnt(7)
	v_cvt_pk_bf16_f32 v50, v24, v25
	v_cvt_pk_bf16_f32 v51, v26, v27
	global_store_dwordx2 v[4:5], v[50:51], off offset:-512
	v_mul_f32_e32 v12, v25, v25
	v_mul_f32_e32 v13, v27, v27
	v_fmac_f32_e32 v12, v24, v24
	v_fmac_f32_e32 v13, v26, v26
	v_add_f32_e32 v12, v12, v13
	v_add_f32_e32 v0, v0, v12
	s_waitcnt vmcnt(7)
	v_cvt_pk_bf16_f32 v52, v28, v29
	v_cvt_pk_bf16_f32 v53, v30, v31
	global_store_dwordx2 v[4:5], v[52:53], off
	v_mul_f32_e32 v12, v29, v29
	v_mul_f32_e32 v13, v31, v31
	v_fmac_f32_e32 v12, v28, v28
	v_fmac_f32_e32 v13, v30, v30
	v_add_f32_e32 v12, v12, v13
	v_add_f32_e32 v0, v0, v12
	s_waitcnt vmcnt(7)
	v_cvt_pk_bf16_f32 v54, v32, v33
	v_cvt_pk_bf16_f32 v55, v34, v35
	global_store_dwordx2 v[4:5], v[54:55], off offset:512
	v_mul_f32_e32 v12, v33, v33
	v_mul_f32_e32 v13, v35, v35
	v_fmac_f32_e32 v12, v32, v32
	v_fmac_f32_e32 v13, v34, v34
	v_add_f32_e32 v12, v12, v13
	v_add_f32_e32 v0, v0, v12
	s_waitcnt vmcnt(7)
	v_cvt_pk_bf16_f32 v56, v36, v37
	v_cvt_pk_bf16_f32 v57, v38, v39
	global_store_dwordx2 v[4:5], v[56:57], off offset:1024
	v_mul_f32_e32 v12, v37, v37
	v_mul_f32_e32 v13, v39, v39
	v_fmac_f32_e32 v12, v36, v36
	v_fmac_f32_e32 v13, v38, v38
	v_add_f32_e32 v12, v12, v13
	v_add_f32_e32 v0, v0, v12
	s_waitcnt vmcnt(7)
	v_mul_f32_e32 v12, v41, v41
	v_mul_f32_e32 v13, v43, v43
	v_fmac_f32_e32 v12, v40, v40
	v_fmac_f32_e32 v13, v42, v42
	v_add_f32_e32 v12, v12, v13
	v_add_f32_e32 v0, v0, v12
	ds_bpermute_b32 v12, v6, v0
	v_cvt_pk_bf16_f32 v58, v40, v41
	v_cvt_pk_bf16_f32 v59, v42, v43
	global_store_dwordx2 v[4:5], v[58:59], off offset:1536
	s_waitcnt lgkmcnt(0)
	v_add_f32_e32 v0, v0, v12
	ds_bpermute_b32 v12, v7, v0
	s_waitcnt lgkmcnt(0)
	v_add_f32_e32 v0, v0, v12
	ds_bpermute_b32 v12, v8, v0
	s_waitcnt lgkmcnt(0)
	v_add_f32_e32 v0, v0, v12
	ds_bpermute_b32 v12, v9, v0
	s_waitcnt lgkmcnt(0)
	v_add_f32_e32 v0, v0, v12
	ds_bpermute_b32 v12, v10, v0
	s_waitcnt lgkmcnt(0)
	v_add_f32_e32 v0, v0, v12
	ds_bpermute_b32 v12, v11, v0
	s_and_saveexec_b64 s[12:13], s[6:7]
	s_cbranch_execz .LBB0_169
	s_waitcnt lgkmcnt(0)
	v_add_f32_e32 v0, v0, v12
	v_fma_f32 v0, v0, s81, 0.5
	v_trunc_f32_e32 v0, v0
	v_mul_f32_e32 v12, 0x2f800000, v0
	v_floor_f32_e32 v13, v12
	v_fmac_f32_e32 v0, 0xcf800000, v13
	v_cvt_u32_f32_e32 v12, v0
	v_cvt_u32_f32_e32 v13, v13
	global_store_dwordx2 v1, v[12:13], s[10:11]
	s_branch .LBB0_169
